# conversion seam allocation 1x2,2,5x2,6x2 (two items in flight at global seams 1,5,6; group seam 2 single) on top of v151
# speedup vs baseline: 1.0022x; 1.0022x over previous
.Lmy_cv1_entry:
	s_mov_b64 exec, -1
	s_cmpk_lg_i32 s3, 0x100
	s_cbranch_scc1 .Lmy_cv1_done
	v_readfirstlane_b32 s30, v0
	s_nop 0
	s_lshr_b32 s30, s30, 6
	s_mul_i32 s7, s2, 7
	s_add_i32 s30, s30, s7
	s_add_i32 s30, s30, 12287
	s_cmp_gt_u32 s30, 0x5fff
	s_cbranch_scc1 .Lmy_cv1_done
	s_mov_b32 s6, s30
	v_and_b32_e32 v1, 63, v0
	v_readlane_b32 s10, v254, 2
	v_readlane_b32 s11, v254, 3
	s_sub_u32 s10, s10, 0xc8
	s_subb_u32 s11, s11, 0
	s_cmp_lt_u32 s6, 0x1600
	s_cbranch_scc1 .Lmy_cv1a_g1
	s_cmp_lt_u32 s6, 0x2c00
	s_cbranch_scc1 .Lmy_cv1a_u1
	s_cmp_lt_u32 s6, 0x3400
	s_cbranch_scc1 .Lmy_cv1a_wo
	s_cmp_lt_u32 s6, 0x4a00
	s_cbranch_scc1 .Lmy_cv1a_g2
	s_load_dwordx2 s[12:13], s[10:11], 0xa0
	s_sub_u32 s6, s6, 0x4a00
	s_movk_i32 s14, 0x80
	s_mov_b32 s20, 0x6a00000
	s_branch .Lmy_cv1a_gu

.Lmy_cv1a_go:
	s_add_u32 s20, s50, s20
	s_addc_u32 s21, s51, 0
	v_and_b32_e32 v2, 7, v1
	v_lshrrev_b32_e32 v3, 3, v1
	s_lshl_b32 s24, s15, 6
	v_lshl_add_u32 v4, v2, 3, s24
	v_mul_lo_u32 v4, v4, s19
	v_lshl_add_u32 v5, v3, 2, s17
	v_add_u32_e32 v4, v4, v5
	v_mov_b32_e32 v5, 0
	v_lshlrev_b64 v[4:5], 2, v[4:5]
	s_lshl_b32 s26, s19, 2
	s_mov_b32 s27, 0
	s_lshr_b32 s28, s18, 8
	s_and_b32 s29, s18, 0xff
	s_lshl_b32 s28, s28, 5
	s_add_u32 s28, s28, s15
	s_lshl_b32 s28, s28, 8
	s_add_u32 s28, s28, s29
	s_waitcnt lgkmcnt(0)
	v_lshl_add_u64 v[4:5], s[12:13], 0, v[4:5]
	global_load_dwordx4 v[8:11], v[4:5], off nt
	v_lshl_add_u64 v[4:5], v[4:5], 0, s[26:27]
	global_load_dwordx4 v[12:15], v[4:5], off nt
	v_lshl_add_u64 v[4:5], v[4:5], 0, s[26:27]
	global_load_dwordx4 v[16:19], v[4:5], off nt
	v_lshl_add_u64 v[4:5], v[4:5], 0, s[26:27]
	global_load_dwordx4 v[20:23], v[4:5], off nt
	v_lshl_add_u64 v[4:5], v[4:5], 0, s[26:27]
	global_load_dwordx4 v[24:27], v[4:5], off nt
	v_lshl_add_u64 v[4:5], v[4:5], 0, s[26:27]
	global_load_dwordx4 v[28:31], v[4:5], off nt
	v_lshl_add_u64 v[4:5], v[4:5], 0, s[26:27]
	global_load_dwordx4 v[32:35], v[4:5], off nt
	v_lshl_add_u64 v[4:5], v[4:5], 0, s[26:27]
	global_load_dwordx4 v[36:39], v[4:5], off nt
	v_lshl_add_u32 v6, v3, 2, s28
	v_lshlrev_b32_e32 v6, 7, v6
	v_lshl_add_u32 v6, v2, 4, v6
	v_mov_b32_e32 v7, 0
	v_lshl_add_u64 v[6:7], s[20:21], 0, v[6:7]
	s_add_i32 s6, s30, 1792
	s_cmp_gt_u32 s6, 0x5fff
	s_cbranch_scc1 .Lmy_cv1_one
	v_and_b32_e32 v1, 63, v0
	v_readlane_b32 s10, v254, 2
	v_readlane_b32 s11, v254, 3
	s_sub_u32 s10, s10, 0xc8
	s_subb_u32 s11, s11, 0
	s_cmp_lt_u32 s6, 0x1600
	s_cbranch_scc1 .Lmy_cv1b_g1
	s_cmp_lt_u32 s6, 0x2c00
	s_cbranch_scc1 .Lmy_cv1b_u1
	s_cmp_lt_u32 s6, 0x3400
	s_cbranch_scc1 .Lmy_cv1b_wo
	s_cmp_lt_u32 s6, 0x4a00
	s_cbranch_scc1 .Lmy_cv1b_g2
	s_load_dwordx2 s[12:13], s[10:11], 0xa0
	s_sub_u32 s6, s6, 0x4a00
	s_movk_i32 s14, 0x80
	s_mov_b32 s20, 0x6a00000
	s_branch .Lmy_cv1b_gu

.Lmy_cv1b_go:
	s_add_u32 s20, s50, s20
	s_addc_u32 s21, s51, 0
	v_and_b32_e32 v2, 7, v1
	v_lshrrev_b32_e32 v3, 3, v1
	s_lshl_b32 s24, s15, 6
	v_lshl_add_u32 v4, v2, 3, s24
	v_mul_lo_u32 v4, v4, s19
	v_lshl_add_u32 v5, v3, 2, s17
	v_add_u32_e32 v4, v4, v5
	v_mov_b32_e32 v5, 0
	v_lshlrev_b64 v[4:5], 2, v[4:5]
	s_lshl_b32 s26, s19, 2
	s_mov_b32 s27, 0
	s_lshr_b32 s28, s18, 8
	s_and_b32 s29, s18, 0xff
	s_lshl_b32 s28, s28, 5
	s_add_u32 s28, s28, s15
	s_lshl_b32 s28, s28, 8
	s_add_u32 s28, s28, s29
	s_waitcnt lgkmcnt(0)
	v_lshl_add_u64 v[4:5], s[12:13], 0, v[4:5]
	global_load_dwordx4 v[64:67], v[4:5], off nt
	v_lshl_add_u64 v[4:5], v[4:5], 0, s[26:27]
	global_load_dwordx4 v[68:71], v[4:5], off nt
	v_lshl_add_u64 v[4:5], v[4:5], 0, s[26:27]
	global_load_dwordx4 v[72:75], v[4:5], off nt
	v_lshl_add_u64 v[4:5], v[4:5], 0, s[26:27]
	global_load_dwordx4 v[76:79], v[4:5], off nt
	v_lshl_add_u64 v[4:5], v[4:5], 0, s[26:27]
	global_load_dwordx4 v[80:83], v[4:5], off nt
	v_lshl_add_u64 v[4:5], v[4:5], 0, s[26:27]
	global_load_dwordx4 v[84:87], v[4:5], off nt
	v_lshl_add_u64 v[4:5], v[4:5], 0, s[26:27]
	global_load_dwordx4 v[88:91], v[4:5], off nt
	v_lshl_add_u64 v[4:5], v[4:5], 0, s[26:27]
	global_load_dwordx4 v[92:95], v[4:5], off nt
	v_lshl_add_u32 v62, v3, 2, s28
	v_lshlrev_b32_e32 v62, 7, v62
	v_lshl_add_u32 v62, v2, 4, v62
	v_mov_b32_e32 v63, 0
	v_lshl_add_u64 v[62:63], s[20:21], 0, v[62:63]
	s_waitcnt vmcnt(8)
	v_cvt_pk_bf16_f32 v40, v8, v12
	v_cvt_pk_bf16_f32 v41, v16, v20
	v_cvt_pk_bf16_f32 v42, v24, v28
	v_cvt_pk_bf16_f32 v43, v32, v36
	global_store_dwordx4 v[6:7], v[40:43], off sc1
	v_cvt_pk_bf16_f32 v44, v9, v13
	v_cvt_pk_bf16_f32 v45, v17, v21
	v_cvt_pk_bf16_f32 v46, v25, v29
	v_cvt_pk_bf16_f32 v47, v33, v37
	global_store_dwordx4 v[6:7], v[44:47], off offset:128 sc1
	v_cvt_pk_bf16_f32 v48, v10, v14
	v_cvt_pk_bf16_f32 v49, v18, v22
	v_cvt_pk_bf16_f32 v50, v26, v30
	v_cvt_pk_bf16_f32 v51, v34, v38
	global_store_dwordx4 v[6:7], v[48:51], off offset:256 sc1
	v_cvt_pk_bf16_f32 v52, v11, v15
	v_cvt_pk_bf16_f32 v53, v19, v23
	v_cvt_pk_bf16_f32 v54, v27, v31
	v_cvt_pk_bf16_f32 v55, v35, v39
	global_store_dwordx4 v[6:7], v[52:55], off offset:384 sc1
	s_waitcnt vmcnt(4)
	v_cvt_pk_bf16_f32 v96, v64, v68
	v_cvt_pk_bf16_f32 v97, v72, v76
	v_cvt_pk_bf16_f32 v98, v80, v84
	v_cvt_pk_bf16_f32 v99, v88, v92
	global_store_dwordx4 v[62:63], v[96:99], off sc1
	v_cvt_pk_bf16_f32 v100, v65, v69
	v_cvt_pk_bf16_f32 v101, v73, v77
	v_cvt_pk_bf16_f32 v102, v81, v85
	v_cvt_pk_bf16_f32 v103, v89, v93
	global_store_dwordx4 v[62:63], v[100:103], off offset:128 sc1
	v_cvt_pk_bf16_f32 v104, v66, v70
	v_cvt_pk_bf16_f32 v105, v74, v78
	v_cvt_pk_bf16_f32 v106, v82, v86
	v_cvt_pk_bf16_f32 v107, v90, v94
	global_store_dwordx4 v[62:63], v[104:107], off offset:256 sc1
	v_cvt_pk_bf16_f32 v108, v67, v71
	v_cvt_pk_bf16_f32 v109, v75, v79
	v_cvt_pk_bf16_f32 v110, v83, v87
	v_cvt_pk_bf16_f32 v111, v91, v95
	global_store_dwordx4 v[62:63], v[108:111], off offset:384 sc1
	s_branch .Lmy_cv1_fin

.Lmy_cv1_fin:
.Lmy_cv1_done:
	s_branch .LBB0_250

.LBB0_355:
	s_or_b64 exec, exec, s[12:13]
	s_waitcnt vmcnt(0)
	s_branch .LBB0_356
.Lmy_cv2_entry:
	s_mov_b64 exec, -1
	s_cmpk_lg_i32 s3, 0x100
	s_cbranch_scc1 .Lmy_cv2_done
	v_readfirstlane_b32 s6, v0
	s_nop 0
	s_lshr_b32 s6, s6, 6
	s_mul_i32 s7, s2, 7
	s_add_i32 s6, s6, s7
	s_add_i32 s6, s6, 15871
	s_cmp_gt_u32 s6, 0x5fff
	s_cbranch_scc1 .Lmy_cv2_done
	v_and_b32_e32 v1, 63, v0
	v_readlane_b32 s10, v254, 2
	v_readlane_b32 s11, v254, 3
	s_sub_u32 s10, s10, 0xc8
	s_subb_u32 s11, s11, 0
	s_cmp_lt_u32 s6, 0x1600
	s_cbranch_scc1 .Lmy_cv2_g1
	s_cmp_lt_u32 s6, 0x2c00
	s_cbranch_scc1 .Lmy_cv2_u1
	s_cmp_lt_u32 s6, 0x3400
	s_cbranch_scc1 .Lmy_cv2_wo
	s_cmp_lt_u32 s6, 0x4a00
	s_cbranch_scc1 .Lmy_cv2_g2
	s_load_dwordx2 s[12:13], s[10:11], 0xa0
	s_sub_u32 s6, s6, 0x4a00
	s_movk_i32 s14, 0x80
	s_mov_b32 s20, 0x6a00000
	s_branch .Lmy_cv2_gu

.Lmy_cv5_entry:
	s_mov_b64 exec, -1
	s_cmpk_lg_i32 s3, 0x100
	s_cbranch_scc1 .Lmy_cv5_done
	v_readfirstlane_b32 s30, v0
	s_nop 0
	s_lshr_b32 s30, s30, 6
	s_mul_i32 s7, s2, 7
	s_add_i32 s30, s30, s7
	s_add_i32 s30, s30, 17663
	s_cmp_gt_u32 s30, 0x5fff
	s_cbranch_scc1 .Lmy_cv5_done
	s_mov_b32 s6, s30
	v_and_b32_e32 v1, 63, v0
	v_readlane_b32 s10, v254, 2
	v_readlane_b32 s11, v254, 3
	s_sub_u32 s10, s10, 0xc8
	s_subb_u32 s11, s11, 0
	s_cmp_lt_u32 s6, 0x1600
	s_cbranch_scc1 .Lmy_cv5a_g1
	s_cmp_lt_u32 s6, 0x2c00
	s_cbranch_scc1 .Lmy_cv5a_u1
	s_cmp_lt_u32 s6, 0x3400
	s_cbranch_scc1 .Lmy_cv5a_wo
	s_cmp_lt_u32 s6, 0x4a00
	s_cbranch_scc1 .Lmy_cv5a_g2
	s_load_dwordx2 s[12:13], s[10:11], 0xa0
	s_sub_u32 s6, s6, 0x4a00
	s_movk_i32 s14, 0x80
	s_mov_b32 s20, 0x6a00000
	s_branch .Lmy_cv5a_gu

.Lmy_cv6_entry:
	s_mov_b64 exec, -1
	s_cmpk_lg_i32 s3, 0x100
	s_cbranch_scc1 .Lmy_cv6_done
	v_readfirstlane_b32 s30, v0
	s_nop 0
	s_lshr_b32 s30, s30, 6
	s_mul_i32 s7, s2, 7
	s_add_i32 s30, s30, s7
	s_add_i32 s30, s30, 21247
	s_cmp_gt_u32 s30, 0x5fff
	s_cbranch_scc1 .Lmy_cv6_done
	s_mov_b32 s6, s30
	v_and_b32_e32 v1, 63, v0
	v_readlane_b32 s10, v254, 2
	v_readlane_b32 s11, v254, 3
	s_sub_u32 s10, s10, 0xc8
	s_subb_u32 s11, s11, 0
	s_cmp_lt_u32 s6, 0x1600
	s_cbranch_scc1 .Lmy_cv6a_g1
	s_cmp_lt_u32 s6, 0x2c00
	s_cbranch_scc1 .Lmy_cv6a_u1
	s_cmp_lt_u32 s6, 0x3400
	s_cbranch_scc1 .Lmy_cv6a_wo
	s_cmp_lt_u32 s6, 0x4a00
	s_cbranch_scc1 .Lmy_cv6a_g2
	s_load_dwordx2 s[12:13], s[10:11], 0xa0
	s_sub_u32 s6, s6, 0x4a00
	s_movk_i32 s14, 0x80
	s_mov_b32 s20, 0x6a00000
	s_branch .Lmy_cv6a_gu

.Lmy_cv6_one:
	s_waitcnt vmcnt(0)
	v_cvt_pk_bf16_f32 v40, v8, v12
	v_cvt_pk_bf16_f32 v41, v16, v20
	v_cvt_pk_bf16_f32 v42, v24, v28
	v_cvt_pk_bf16_f32 v43, v32, v36
	global_store_dwordx4 v[6:7], v[40:43], off sc1
	v_cvt_pk_bf16_f32 v44, v9, v13
	v_cvt_pk_bf16_f32 v45, v17, v21
	v_cvt_pk_bf16_f32 v46, v25, v29
	v_cvt_pk_bf16_f32 v47, v33, v37
	global_store_dwordx4 v[6:7], v[44:47], off offset:128 sc1
	v_cvt_pk_bf16_f32 v48, v10, v14
	v_cvt_pk_bf16_f32 v49, v18, v22
	v_cvt_pk_bf16_f32 v50, v26, v30
	v_cvt_pk_bf16_f32 v51, v34, v38
	global_store_dwordx4 v[6:7], v[48:51], off offset:256 sc1
	v_cvt_pk_bf16_f32 v52, v11, v15
	v_cvt_pk_bf16_f32 v53, v19, v23
	v_cvt_pk_bf16_f32 v54, v27, v31
	v_cvt_pk_bf16_f32 v55, v35, v39
	global_store_dwordx4 v[6:7], v[52:55], off offset:384 sc1
.Lmy_cv6_fin:
	s_waitcnt vmcnt(0)
.Lmy_cv6_done:
	s_branch .LBB0_780
